# attention: s_setprio 1 only around the PV+QK MFMA sections of each wave, 0 elsewhere
# baseline (speedup 1.0000x reference)
.Lat_nosq5:
.Lat_x_nostore:
	s_setprio 1
	s_cmp_gt_i32 s22, s25
	s_cbranch_scc1 .Lat_x_nopre
	s_mul_i32 s36, s24, 0x6400
	v_add_u32_e32 v0, s36, v230
	ds_read_b128 v[162:165], v0
	ds_read_b128 v[166:169], v0 offset:12800
	ds_read_b128 v[170:173], v0 offset:32
	ds_read_b128 v[174:177], v0 offset:12832
	ds_read_b128 v[178:181], v0 offset:64
	ds_read_b128 v[182:185], v0 offset:12864
	ds_read_b128 v[186:189], v0 offset:96
	ds_read_b128 v[190:193], v0 offset:12896

.Lat_x_pref:
	s_setprio 0
	s_add_i32 s65, s22, 1
	s_cmp_lg_u32 s65, s23
	s_cbranch_scc1 .Lat_x_nopf
	s_cmp_eq_u32 s26, 2
	s_cbranch_scc1 .Lat_x_nopf
	s_cmp_eq_u32 s26, 0
	s_cbranch_scc1 .Lat_x_pf1
	s_cmp_lg_u32 s31, 0
	s_cbranch_scc1 .Lat_x_nopf
	s_mov_b32 s4, 0
	s_branch .Lat_x_pf
